# attn: staging LDS addresses precomputed once per q block instead of per key tile (-80 VALU/iter); HGRN gain vector via LDS
# speedup vs baseline: 1.0009x; 1.0009x over previous
; #define LAS __attribute__((address_space(3)))
; __device__ __forceinline__ void hgrn_unit(const bf16_t* P, bf16_t* Y, const float* lb, const float* hgn, LAS unsigned char* lds, int bl, int h, int tid) {
;     const int lane = tid & 63, w = __builtin_amdgcn_readfirstlane(tid >> 6), fr = lane & 15, fq = lane >> 4;
;     const int k = tid & 127, seg = tid >> 7, tt = w & 3, vh = w >> 2;
;     const float lbk = lb[h * 128 + k];
;     for (int i = tid; i < 128 * ST_S / 16; i += 512) *(LAS u32x4*)(lds + OFF_ST + i * 16) = (u32x4){0u, 0u, 0u, 0u};
;     f32x4 S[8];
; #pragma unroll
;     for (int i = 0; i < 8; ++i) S[i] = (f32x4){0.f, 0.f, 0.f, 0.f};
;     const bf16_t* Pb = P + (size_t)bl * SEQ * NHC + h * 128;
;     unsigned short rq[16], rf[16], ri[16];
;     { const bf16_t* p = Pb + (size_t)(seg * 16) * NHC + k;
; #pragma unroll
;       for (int j = 0; j < 16; ++j) { rq[j] = p[(size_t)j * NHC + C_HQ]; rf[j] = p[(size_t)j * NHC + C_HF]; ri[j] = p[(size_t)j * NHC + C_HI]; } }
;     LAS float* segs = (LAS float*)(lds + OFF_SEG); LAS float* decs = (LAS float*)(lds + OFF_DEC); LAS float* ssq = (LAS float*)(lds + OFF_SSQ);
;     const float oml = 1.f - lbk; constexpr float L2E = 1.4426950408889634f;
;     float c[16], om[16]; f32x4 o[4]; u32x2 rz[4];
.LBB0_206:
	s_or_b64 exec, exec, s[4:5]
	s_ashr_i32 s46, s92, 3
	s_ashr_i32 s3, s18, 6
	s_ashr_i32 s47, s46, 31
	s_and_b32 s35, s3, 3
	s_ashr_i32 s19, s18, 8
	s_lshl_b64 s[50:51], s[46:47], 26
	s_add_u32 s1, s48, s50
	s_addc_u32 s4, s49, s51
	s_lshl_b32 s5, s0, 1
	v_ashrrev_i32_e32 v6, 7, v4
	s_add_u32 s1, s1, s5
	s_addc_u32 s4, s4, 0
	v_lshlrev_b32_e32 v52, 4, v6
	s_add_u32 s14, s1, 0x19a5100
	v_ashrrev_i32_e32 v53, 31, v52
	s_addc_u32 s15, s4, 0
	v_lshlrev_b64 v[0:1], 13, v[52:53]
	v_lshl_add_u64 v[2:3], s[14:15], 0, v[0:1]
	v_lshlrev_b32_e32 v0, 1, v5
	v_mov_b32_e32 v1, 0
	v_lshl_add_u64 v[2:3], v[2:3], 0, v[0:1]
	s_movk_i32 s1, 0x2000
	v_add_co_u32_e32 v12, vcc, s1, v2
	s_movk_i32 s1, 0x4000
	s_nop 0
	v_addc_co_u32_e32 v13, vcc, 0, v3, vcc
	v_add_co_u32_e32 v14, vcc, s1, v2
	s_mov_b32 s1, 0x1f000
	s_nop 0
	v_addc_co_u32_e32 v15, vcc, 0, v3, vcc
	v_add_co_u32_e32 v16, vcc, s1, v2
	s_movk_i32 s1, 0x6000
	s_nop 0
	v_addc_co_u32_e32 v17, vcc, 0, v3, vcc
	global_load_ushort v7, v[2:3], off
	global_load_ushort v91, v[12:13], off offset:-4096
	global_load_ushort v9, v[12:13], off
	global_load_ushort v92, v[14:15], off offset:-4096
	global_load_ushort v10, v[14:15], off
	global_load_ushort v11, v[12:13], off offset:2048
	global_load_ushort v90, v[16:17], off
	global_load_ushort v28, v[2:3], off offset:2048
	v_add_co_u32_e32 v12, vcc, s1, v2
	s_mov_b32 s1, 0x8000
	s_nop 0
	v_addc_co_u32_e32 v13, vcc, 0, v3, vcc
	v_add_co_u32_e32 v16, vcc, s1, v2
	s_mov_b32 s1, 0xa000
	s_nop 0
	v_addc_co_u32_e32 v17, vcc, 0, v3, vcc
	v_add_co_u32_e32 v18, vcc, s1, v2
	s_mov_b32 s1, 0xc000
	s_nop 0
	v_addc_co_u32_e32 v19, vcc, 0, v3, vcc
	global_load_ushort v94, v[12:13], off offset:-4096
	global_load_ushort v29, v[12:13], off
	global_load_ushort v96, v[16:17], off offset:-4096
	global_load_ushort v30, v[16:17], off
	global_load_ushort v93, v[18:19], off offset:-4096
	global_load_ushort v31, v[16:17], off offset:2048
	global_load_ushort v32, v[12:13], off offset:2048
	global_load_ushort v33, v[14:15], off offset:2048
	v_add_co_u32_e32 v20, vcc, s1, v2
	s_mov_b32 s1, 0xe000
	s_nop 0
	v_addc_co_u32_e32 v21, vcc, 0, v3, vcc
	v_add_co_u32_e32 v22, vcc, s1, v2
	s_mov_b32 s1, 0x10000
	s_nop 0
	v_addc_co_u32_e32 v23, vcc, 0, v3, vcc
	global_load_ushort v34, v[18:19], off
	global_load_ushort v105, v[20:21], off offset:-4096
	global_load_ushort v35, v[20:21], off
	global_load_ushort v98, v[22:23], off offset:-4096
	global_load_ushort v36, v[22:23], off
	global_load_ushort v37, v[22:23], off offset:2048
	global_load_ushort v38, v[20:21], off offset:2048
	global_load_ushort v39, v[18:19], off offset:2048
	v_add_co_u32_e32 v12, vcc, s1, v2
	s_mov_b32 s1, 0x12000
	s_nop 0
	v_addc_co_u32_e32 v13, vcc, 0, v3, vcc
	v_add_co_u32_e32 v14, vcc, s1, v2
	s_mov_b32 s1, 0x14000
	s_nop 0
	v_addc_co_u32_e32 v15, vcc, 0, v3, vcc
	v_add_co_u32_e32 v16, vcc, s1, v2
	s_mov_b32 s1, 0x16000
	s_nop 0
	v_addc_co_u32_e32 v17, vcc, 0, v3, vcc
	v_add_co_u32_e32 v24, vcc, s1, v2
	s_mov_b32 s1, 0x18000
	s_nop 0
	v_addc_co_u32_e32 v25, vcc, 0, v3, vcc
	v_add_co_u32_e32 v26, vcc, s1, v2
	s_mov_b32 s1, 0x1a000
	s_nop 0
	v_addc_co_u32_e32 v27, vcc, 0, v3, vcc
	v_add_co_u32_e32 v18, vcc, s1, v2
	s_waitcnt vmcnt(0)
	v_sub_f32_e32 v54, 1.0, v65
	v_addc_co_u32_e32 v19, vcc, 0, v3, vcc
	s_mov_b32 s1, 0x1c000
	v_add_co_u32_e32 v20, vcc, s1, v2
	s_mov_b32 s1, 0x1e000
	s_nop 0
	v_addc_co_u32_e32 v21, vcc, 0, v3, vcc
	v_add_co_u32_e32 v2, vcc, s1, v2
	v_mov_b32_e32 v55, v54
	s_nop 0
	v_addc_co_u32_e32 v3, vcc, 0, v3, vcc
	s_add_i32 s5, 0, 0x1c400
	v_lshl_add_u32 v95, v4, 2, s5
	v_and_b32_e32 v53, 15, v8
	v_bfe_u32 v8, v8, 4, 2
	s_lshl_b32 s3, s3, 4
	v_lshl_add_u64 v[62:63], s[14:15], 0, v[0:1]
	v_lshlrev_b32_e32 v99, 4, v8
	s_add_i32 s20, 0, 0x1ce00
	s_lshl_b32 s4, s19, 6
	v_lshlrev_b32_e32 v11, 16, v11
	v_mul_f32_e32 v11, 0xbfb8aa3b, v11
	v_lshlrev_b32_e32 v22, 16, v28
	global_load_ushort v110, v[12:13], off offset:-4096
	global_load_ushort v28, v[12:13], off
	global_load_ushort v107, v[14:15], off offset:-4096
	global_load_ushort v40, v[14:15], off
	global_load_ushort v109, v[16:17], off offset:-4096
	global_load_ushort v41, v[16:17], off
	global_load_ushort v42, v[14:15], off offset:2048
	global_load_ushort v43, v[12:13], off offset:2048
	v_exp_f32_e32 v11, v11
	v_mul_f32_e32 v22, 0xbfb8aa3b, v22
	v_exp_f32_e32 v22, v22
	s_and_b32 s18, s18, 0xffffff00
	v_add_f32_e32 v11, 1.0, v11
	v_rcp_f32_e32 v23, v11
	global_load_ushort v111, v[24:25], off offset:-4096
	global_load_ushort v11, v[24:25], off
	global_load_ushort v112, v[26:27], off offset:-4096
	global_load_ushort v14, v[26:27], off
	global_load_ushort v108, v[18:19], off offset:-4096
	global_load_ushort v15, v[26:27], off offset:2048
	global_load_ushort v44, v[24:25], off offset:2048
	global_load_ushort v45, v[16:17], off offset:2048
	v_add_f32_e32 v22, 1.0, v22
	v_rcp_f32_e32 v22, v22
	s_add_i32 s18, s20, s18
	s_lshl_b32 s1, s35, 4
	s_lshl_b32 s22, s19, 1
	v_fma_f32 v12, v54, v22, v65
	v_log_f32_e32 v12, v12
	v_pk_fma_f32 v[48:49], v[54:55], v[22:23], v[54:55] op_sel_hi:[0,1,0] neg_lo:[1,0,0] neg_hi:[1,0,0]
	v_lshlrev_b32_e32 v13, 16, v33
	v_mul_f32_e32 v13, 0xbfb8aa3b, v13
	v_add_f32_e32 v130, 0, v12
	v_fma_f32 v12, v54, v23, v65
	global_load_ushort v16, v[18:19], off
	global_load_ushort v129, v[20:21], off offset:-4096
	global_load_ushort v17, v[20:21], off
	global_load_ushort v113, v[2:3], off offset:-4096
	global_load_ushort v22, v[2:3], off
	global_load_ushort v23, v[2:3], off offset:2048
	global_load_ushort v24, v[20:21], off offset:2048
	global_load_ushort v25, v[18:19], off offset:2048
	v_log_f32_e32 v12, v12
	v_exp_f32_e32 v13, v13
	v_cmp_lt_i32_e64 s[6:7], 0, v6
	v_cmp_lt_i32_e64 s[8:9], 1, v6
	v_add_f32_e32 v131, v130, v12
	v_add_f32_e32 v12, 1.0, v13
	v_lshlrev_b32_e32 v13, 16, v32
	v_mul_f32_e32 v13, 0xbfb8aa3b, v13
	v_exp_f32_e32 v13, v13
	v_rcp_f32_e32 v12, v12
	v_cmp_lt_i32_e64 s[10:11], 2, v6
	s_movk_i32 s23, 0x90
	v_add_f32_e32 v3, 1.0, v13
	v_rcp_f32_e32 v13, v3
	v_lshlrev_b32_e32 v3, 16, v31
	v_mul_f32_e32 v3, 0xbfb8aa3b, v3
	v_exp_f32_e32 v3, v3
	v_fma_f32 v2, v54, v12, v65
	v_log_f32_e32 v18, v2
	v_fma_f32 v2, v54, v13, v65
	v_log_f32_e32 v19, v2
	v_add_f32_e32 v2, 1.0, v3
	v_pk_fma_f32 v[82:83], v[54:55], v[12:13], v[54:55] op_sel_hi:[0,1,0] neg_lo:[1,0,0] neg_hi:[1,0,0]
	v_lshlrev_b32_e32 v12, 16, v39
	v_rcp_f32_e32 v2, v2
	v_mul_f32_e32 v12, 0xbfb8aa3b, v12
	v_exp_f32_e32 v12, v12
	v_lshlrev_b32_e32 v13, 16, v38
	v_fma_f32 v3, v54, v2, v65
	v_add_f32_e32 v139, v131, v18
	v_mul_f32_e32 v13, 0xbfb8aa3b, v13
	v_log_f32_e32 v18, v3
	v_add_f32_e32 v3, 1.0, v12
	v_exp_f32_e32 v13, v13
	v_rcp_f32_e32 v3, v3
	v_add_f32_e32 v140, v139, v19
	v_lshlrev_b32_e32 v19, 16, v37
	v_mul_f32_e32 v19, 0xbfb8aa3b, v19
	v_add_f32_e32 v12, 1.0, v13
	v_fma_f32 v13, v54, v3, v65
	v_exp_f32_e32 v19, v19
	v_log_f32_e32 v13, v13
	v_add_f32_e32 v138, v140, v18
	v_pk_fma_f32 v[86:87], v[54:55], v[2:3], v[54:55] op_sel_hi:[0,1,0] neg_lo:[1,0,0] neg_hi:[1,0,0]
	v_add_f32_e32 v2, 1.0, v19
	v_add_f32_e32 v142, v138, v13
	v_rcp_f32_e32 v13, v2
	v_rcp_f32_e32 v12, v12
	s_movk_i32 s21, 0x110
	s_mov_b32 s52, 0xfffe0000
	v_fma_f32 v3, v54, v13, v65
	v_fma_f32 v18, v54, v12, v65
	v_log_f32_e32 v18, v18
	v_pk_fma_f32 v[78:79], v[54:55], v[12:13], v[54:55] op_sel_hi:[0,1,0] neg_lo:[1,0,0] neg_hi:[1,0,0]
	v_log_f32_e32 v3, v3
	s_mov_b32 s53, -1
	v_add_f32_e32 v132, v142, v18
	v_xor_b32_e32 v58, 0x80000000, v54
	s_waitcnt vmcnt(17)
	v_lshlrev_b32_e32 v12, 16, v42
	s_waitcnt vmcnt(16)
	v_lshlrev_b32_e32 v2, 16, v43
	v_mul_f32_e32 v2, 0xbfb8aa3b, v2
	v_exp_f32_e32 v2, v2
	v_mul_f32_e32 v12, 0xbfb8aa3b, v12
	v_exp_f32_e32 v12, v12
	v_add_f32_e32 v141, v132, v3
	v_add_f32_e32 v2, 1.0, v2
	v_rcp_f32_e32 v2, v2
	s_waitcnt vmcnt(10)
	v_lshlrev_b32_e32 v15, 16, v15
	v_mul_f32_e32 v15, 0xbfb8aa3b, v15
	v_exp_f32_e32 v15, v15
	v_fma_f32 v3, v54, v2, v65
	v_log_f32_e32 v13, v3
	v_add_f32_e32 v3, 1.0, v12
	v_rcp_f32_e32 v3, v3
	s_waitcnt vmcnt(8)
	v_lshlrev_b32_e32 v12, 16, v45
	v_mul_f32_e32 v12, 0xbfb8aa3b, v12
	v_exp_f32_e32 v12, v12
	v_add_f32_e32 v136, v141, v13
	v_fma_f32 v13, v54, v3, v65
	v_pk_fma_f32 v[80:81], v[54:55], v[2:3], v[54:55] op_sel_hi:[0,1,0] neg_lo:[1,0,0] neg_hi:[1,0,0]
	v_lshlrev_b32_e32 v3, 16, v44
	v_mul_f32_e32 v3, 0xbfb8aa3b, v3
	v_add_f32_e32 v2, 1.0, v12
	v_exp_f32_e32 v3, v3
	v_rcp_f32_e32 v2, v2
	v_log_f32_e32 v12, v13
	v_mul_u32_u24_e32 v31, 0x90, v53
	v_add_f32_e32 v3, 1.0, v3
	v_fma_f32 v13, v54, v2, v65
	v_rcp_f32_e32 v3, v3
	v_log_f32_e32 v13, v13
	v_add_f32_e32 v145, v136, v12
	v_add_f32_e32 v12, 1.0, v15
	s_waitcnt vmcnt(0)
	v_lshlrev_b32_e32 v15, 16, v25
	v_rcp_f32_e32 v12, v12
	v_mul_f32_e32 v15, 0xbfb8aa3b, v15
	v_pk_fma_f32 v[88:89], v[54:55], v[2:3], v[54:55] op_sel_hi:[0,1,0] neg_lo:[1,0,0] neg_hi:[1,0,0]
	v_lshlrev_b32_e32 v2, 16, v24
	v_add_f32_e32 v135, v145, v13
	v_fma_f32 v13, v54, v3, v65
	v_exp_f32_e32 v15, v15
	v_mul_f32_e32 v2, 0xbfb8aa3b, v2
	v_lshlrev_b32_e32 v3, 16, v23
	v_exp_f32_e32 v2, v2
	v_mul_f32_e32 v3, 0xbfb8aa3b, v3
	v_exp_f32_e32 v3, v3
	v_log_f32_e32 v18, v13
	v_fma_f32 v13, v54, v12, v65
	v_log_f32_e32 v19, v13
	v_add_f32_e32 v13, 1.0, v15
	v_rcp_f32_e32 v13, v13
	v_add_f32_e32 v2, 1.0, v2
	v_rcp_f32_e32 v2, v2
	v_add_f32_e32 v3, 1.0, v3
	v_rcp_f32_e32 v3, v3
	v_fma_f32 v15, v54, v13, v65
	v_pk_fma_f32 v[84:85], v[54:55], v[12:13], v[54:55] op_sel_hi:[0,1,0] neg_lo:[1,0,0] neg_hi:[1,0,0]
	v_log_f32_e32 v12, v15
	v_fma_f32 v13, v54, v2, v65
	v_log_f32_e32 v13, v13
	v_fma_f32 v15, v54, v3, v65
	v_add_f32_e32 v143, v135, v18
	v_log_f32_e32 v15, v15
	v_add_f32_e32 v133, v143, v19
	v_add_f32_e32 v144, v133, v12
	v_add_f32_e32 v134, v144, v13
	v_lshlrev_b32_e32 v13, 2, v5
	v_add_f32_e32 v137, v134, v15
	v_add_u32_e32 v97, s5, v13
	v_add_u32_e32 v15, 0, v0
	s_movk_i32 s5, 0x8e
	v_mad_u32_u24 v5, v5, s5, v15
	s_movk_i32 s5, 0x80
	v_lshlrev_b32_e32 v12, 2, v8
	v_cmp_gt_u32_e64 s[12:13], s5, v4
	s_add_i32 s5, 0, 0x11800
	v_mov_b32_e32 v0, s5
	s_add_i32 s5, 0, 0x13c00
	v_or_b32_e32 v21, s3, v12
	v_mbcnt_hi_u32_b32 v25, -1, v208
	v_add_u32_e32 v20, s5, v99
	v_lshlrev_b32_e32 v23, 2, v21
	v_lshl_add_u32 v21, v21, 1, s5
	v_and_b32_e32 v27, 64, v25
	s_lshl_b32 s5, s35, 6
	v_pk_fma_f32 v[50:51], v[54:55], v[2:3], v[54:55] op_sel_hi:[0,1,0] neg_lo:[1,0,0] neg_hi:[1,0,0]
	v_lshlrev_b32_e32 v2, 2, v53
	v_xor_b32_e32 v26, 16, v25
	v_add_u32_e32 v27, 64, v27
	s_add_i32 s24, s5, s20
	v_or_b32_e32 v60, s4, v12
	v_cmp_lt_i32_e32 vcc, v26, v27
	v_add_u32_e32 v103, s24, v2
	s_add_i32 s24, 0, 0x1cc00
	s_add_i32 s18, s18, s5
	v_ashrrev_i32_e32 v61, 31, v60
	s_ashr_i32 s5, s4, 31
	v_cndmask_b32_e32 v26, v25, v26, vcc
	v_lshl_add_u64 v[56:57], v[60:61], 2, s[16:17]
	v_lshlrev_b32_e32 v254, 2, v60
	v_add_u32_e32 v254, 0x1d800, v254
	global_load_dwordx4 v[250:253], v[56:57], off
	s_waitcnt vmcnt(0)
; #define LAS __attribute__((address_space(3)))
; __device__ __forceinline__ void hgrn_unit(const bf16_t* P, bf16_t* Y, const float* lb, const float* hgn, LAS unsigned char* lds, int bl, int h, int tid) {
;     ...
;     f32x4 S[8];
; #pragma unroll
;     for (int i = 0; i < 8; ++i) S[i] = (f32x4){0.f, 0.f, 0.f, 0.f};
;     const bf16_t* Pb = P + (size_t)bl * SEQ * NHC + h * 128;
;     unsigned short rq[16], rf[16], ri[16];
;     { const bf16_t* p = Pb + (size_t)(seg * 16) * NHC + k;
; #pragma unroll
;       for (int j = 0; j < 16; ++j) { rq[j] = p[(size_t)j * NHC + C_HQ]; rf[j] = p[(size_t)j * NHC + C_HF]; ri[j] = p[(size_t)j * NHC + C_HI]; } }
;     LAS float* segs = (LAS float*)(lds + OFF_SEG); LAS float* decs = (LAS float*)(lds + OFF_DEC); LAS float* ssq = (LAS float*)(lds + OFF_SSQ);
;     const float oml = 1.f - lbk; constexpr float L2E = 1.4426950408889634f;
;     float c[16], om[16]; f32x4 o[4]; u32x2 rz[4];
	ds_write_b128 v254, v[250:253]
	s_waitcnt lgkmcnt(0)
	global_load_dwordx4 v[250:253], v[56:57], off offset:64
	s_waitcnt vmcnt(0)
	ds_write_b128 v254, v[250:253] offset:64
	s_waitcnt lgkmcnt(0)
	global_load_dwordx4 v[250:253], v[56:57], off offset:128
	s_waitcnt vmcnt(0)
	ds_write_b128 v254, v[250:253] offset:128
	s_waitcnt lgkmcnt(0)
	global_load_dwordx4 v[250:253], v[56:57], off offset:192
	s_waitcnt vmcnt(0)
	ds_write_b128 v254, v[250:253] offset:192
	s_waitcnt lgkmcnt(0)
	s_movk_i32 s16, 0x1100
	s_cmp_le_i32 s22, s35
	v_or_b32_e32 v3, s1, v53
	v_lshlrev_b32_e32 v18, 5, v6
	v_lshlrev_b32_e32 v101, 2, v26
	v_xor_b32_e32 v26, 32, v25
	v_mul_lo_u32 v6, v6, s16
	s_cselect_b64 s[42:43], -1, 0
	s_lshl_b32 s16, s19, 5
	v_mad_u32_u24 v100, v3, s23, v0
	v_or_b32_e32 v0, s4, v53
	v_cmp_lt_i32_e32 vcc, v26, v27
	s_cmp_ge_i32 s22, s35
	v_add_u32_e32 v104, s24, v13
	v_cndmask_b32_e32 v25, v25, v26, vcc
	v_add_u32_e32 v106, s18, v2
	v_or_b32_e32 v2, s16, v53
	s_cselect_b64 s[44:45], -1, 0
	s_or_b32 s24, s16, 16
	v_mul_lo_u32 v26, v0, s21
	v_mul_lo_u32 v27, v0, s23
	v_mov_b32_e32 v0, 0x1200
	v_mul_lo_u32 v13, v2, s21
	v_or_b32_e32 v2, s24, v53
	v_mad_u32_u24 v33, v53, s23, v0
	v_or_b32_e32 v0, s16, v12
	v_lshlrev_b32_e32 v102, 2, v25
	v_mul_lo_u32 v25, v2, s21
	v_or_b32_e32 v2, 2, v0
	v_mad_u32_u24 v4, v3, s21, 0
	v_or_b32_e32 v24, s3, v53
	v_cmp_gt_i32_e64 s[16:17], v0, v3
	v_cmp_lt_i32_e64 s[18:19], v0, v3
	v_cmp_gt_i32_e64 s[20:21], v2, v3
	v_or_b32_e32 v2, 3, v0
	v_lshlrev_b32_e32 v37, 1, v0
	v_or_b32_e32 v0, s24, v12
	v_mul_lo_u32 v24, v24, s23
	v_cmp_gt_i32_e64 s[22:23], v2, v3
	v_or_b32_e32 v2, 2, v0
	s_lshl_b64 s[46:47], s[46:47], 24
	s_lshl_b32 s37, s92, 8
	v_cmp_gt_i32_e64 s[28:29], v2, v3
	v_or_b32_e32 v2, 3, v0
	v_lshl_or_b32 v64, v3, 11, s46
	s_and_b32 s37, s37, 0x700
	v_cmp_gt_i32_e64 s[24:25], v0, v3
	v_cmp_lt_i32_e64 s[26:27], v0, v3
	v_cmp_gt_i32_e64 s[30:31], v2, v3
	v_or_b32_e32 v2, s37, v64
	v_mov_b32_e32 v3, s47
	s_or_b32 s37, s50, s37
	s_lshl_b64 s[4:5], s[4:5], 1
	v_lshl_add_u64 v[2:3], v[60:61], 1, v[2:3]
	s_add_u32 s4, s4, s37
	v_lshlrev_b32_e32 v12, 1, v0
	v_lshl_add_u64 v[2:3], s[40:41], 0, v[2:3]
	s_addc_u32 s5, s5, s51
	v_lshlrev_b32_e32 v0, 13, v53
	v_lshl_add_u64 v[68:69], v[2:3], 0, s[52:53]
	v_lshl_or_b32 v2, v8, 3, s4
	v_mov_b32_e32 v3, s5
	v_lshl_or_b32 v0, s35, 17, v0
	v_lshl_add_u64 v[2:3], v[2:3], 0, v[0:1]
	v_add_u32_e32 v19, 0, v99
	v_add_u32_e32 v24, 0, v24
	v_mul_u32_u24_e32 v32, 0x110, v53
	s_mov_b32 s33, 0x5040100
	v_lshl_add_u64 v[2:3], s[48:49], 0, v[2:3]
	s_mov_b64 s[4:5], 0x19a6940
	v_add_u32_e32 v0, 0, v23
	v_mov_b32_e32 v59, v58
	s_mov_b32 s3, 64
	v_cmp_eq_u32_e64 s[14:15], 0, v8
	v_perm_b32 v153, v9, v7, s33
	v_perm_b32 v152, v29, v10, s33
	v_perm_b32 v151, v34, v30, s33
	v_perm_b32 v150, v36, v35, s33
	v_perm_b32 v149, v40, v28, s33
	v_perm_b32 v148, v11, v41, s33
	v_perm_b32 v147, v16, v14, s33
	v_perm_b32 v146, v22, v17, s33
	v_lshl_add_u64 v[70:71], v[2:3], 0, s[4:5]
	v_mov_b32_e32 v114, 0x358637bd
	s_mov_b32 s35, 0x800000
	v_add_u32_e32 v115, v15, v6
	v_add_u32_e32 v116, v5, v18
	v_add_u32_e32 v117, v4, v99
	v_add_u32_e32 v118, v19, v13
	v_add_u32_e32 v119, v100, v37
	v_add_u32_e32 v120, v19, v25
	v_add_u32_e32 v121, v100, v12
	v_add_u32_e32 v122, v20, v26
	v_add_u32_e32 v123, v19, v27
	v_add_u32_e32 v124, 0x1cc00, v0
	v_add_u32_e32 v125, v24, v99
	v_add_u32_e32 v126, v19, v31
	v_add_u32_e32 v127, v21, v32
	v_add_u32_e32 v128, v19, v33
	s_mov_b64 s[48:49], 0x20000
	s_mov_b64 s[50:51], 0x80000
	v_mov_b32_e32 v0, v1
	v_mov_b32_e32 v2, v1
	v_mov_b32_e32 v3, v1
	v_mov_b32_e32 v4, v1
	v_mov_b32_e32 v5, v1
	v_mov_b32_e32 v6, v1
	v_mov_b32_e32 v7, v1
	v_mov_b32_e32 v8, v1
	v_mov_b32_e32 v9, v1
	v_mov_b32_e32 v10, v1
	v_mov_b32_e32 v11, v1
	v_mov_b32_e32 v12, v1
	v_mov_b32_e32 v13, v1
	v_mov_b32_e32 v14, v1
	v_mov_b32_e32 v15, v1
	v_mov_b32_e32 v16, v1
	v_mov_b32_e32 v17, v1
	v_mov_b32_e32 v18, v1
	v_mov_b32_e32 v19, v1
	v_mov_b32_e32 v20, v1
	v_mov_b32_e32 v21, v1
	v_mov_b32_e32 v22, v1
	v_mov_b32_e32 v23, v1
	v_mov_b32_e32 v24, v1
	v_mov_b32_e32 v25, v1
	v_mov_b32_e32 v26, v1
	v_mov_b32_e32 v27, v1
	v_mov_b32_e32 v28, v1
	v_mov_b32_e32 v29, v1
	v_mov_b32_e32 v30, v1
	v_mov_b32_e32 v31, v1
	v_mov_b32_e32 v44, v1
	v_mov_b32_e32 v45, v1
	v_mov_b32_e32 v46, v1
	v_mov_b32_e32 v47, v1
	v_mov_b32_e32 v40, v1
	v_mov_b32_e32 v41, v1
	v_mov_b32_e32 v42, v1
	v_mov_b32_e32 v43, v1
	v_mov_b32_e32 v36, v1
	v_mov_b32_e32 v37, v1
	v_mov_b32_e32 v38, v1
	v_mov_b32_e32 v39, v1
	v_mov_b32_e32 v32, v1
	v_mov_b32_e32 v33, v1
	v_mov_b32_e32 v34, v1
	v_mov_b32_e32 v35, v1
	v_mov_b32_e32 v76, v1
	v_mov_b32_e32 v77, v1
	v_mov_b32_e32 v74, v1
	v_mov_b32_e32 v75, v1
	v_mov_b32_e32 v72, v1
	v_mov_b32_e32 v73, v1
	v_mov_b32_e32 v66, v1
	v_mov_b32_e32 v67, v1
	ds_write_b32 v95, v137
	s_branch .LBB0_208

; __device__ __forceinline__ void hgrn_unit(const bf16_t* P, bf16_t* Y, const float* lb, const float* hgn, LAS unsigned char* lds, int bl, int h, int tid) {
;     ...
;         __syncthreads();
;         if (n > 0) HG_OUT(t0 - 64);
; #pragma unroll
;         for (int i = 0; i < 4; ++i) rz[i] = *(const u32x2*)(Pb + (size_t)(t0 + tt * 16 + fr) * NHC + C_HZ + (vh * 4 + i) * 16 + 4 * fq);
.LBB0_208:
	s_cmp_eq_u32 s3, 64
	s_waitcnt lgkmcnt(0)
	s_barrier
	s_cbranch_scc1 .LBB0_210
	ds_read_b128 v[154:157], v254
	ds_read2st64_b32 v[158:159], v103 offset1:1
	v_lshlrev_b32_e32 v160, 16, v76
	v_and_b32_e32 v161, 0xffff0000, v76
	v_lshlrev_b32_e32 v76, 16, v77
	v_mul_f32_e32 v162, 0xbfb8aa3b, v160
	v_mul_f32_e32 v164, 0xbfb8aa3b, v76
	v_mul_f32_e32 v163, 0xbfb8aa3b, v161
	v_exp_f32_e32 v162, v162
	v_exp_f32_e32 v164, v164
	v_exp_f32_e32 v163, v163
	v_and_b32_e32 v77, 0xffff0000, v77
	s_waitcnt lgkmcnt(0)
	v_add_f32_e32 v158, v158, v159
	v_mul_f32_e32 v165, 0xbfb8aa3b, v77
	v_fmamk_f32 v166, v158, 0x3c000000, v114
	v_exp_f32_e32 v165, v165
	v_add_f32_e32 v158, 1.0, v162
	v_add_f32_e32 v162, 1.0, v164
	v_mul_f32_e32 v164, 0x4b800000, v166
	v_cmp_gt_f32_e32 vcc, s35, v166
	v_add_f32_e32 v159, 1.0, v163
	v_rcp_f32_e32 v158, v158
	v_cndmask_b32_e32 v164, v166, v164, vcc
	v_rcp_f32_e32 v159, v159
	v_rsq_f32_e32 v164, v164
	v_add_f32_e32 v163, 1.0, v165
	v_rcp_f32_e32 v162, v162
	v_rcp_f32_e32 v163, v163
	v_pk_mul_f32 v[158:159], v[158:159], v[160:161]
	v_mul_f32_e32 v160, 0x45800000, v164
	v_cndmask_b32_e32 v160, v164, v160, vcc
	v_pk_mul_f32 v[44:45], v[44:45], v[160:161] op_sel_hi:[1,0]
	v_pk_mul_f32 v[46:47], v[46:47], v[160:161] op_sel_hi:[1,0]
	v_pk_mul_f32 v[76:77], v[162:163], v[76:77]
	v_pk_mul_f32 v[40:41], v[40:41], v[160:161] op_sel_hi:[1,0]
	v_pk_mul_f32 v[42:43], v[42:43], v[160:161] op_sel_hi:[1,0]
	v_pk_mul_f32 v[36:37], v[36:37], v[160:161] op_sel_hi:[1,0]
	v_pk_mul_f32 v[38:39], v[38:39], v[160:161] op_sel_hi:[1,0]
	v_pk_mul_f32 v[32:33], v[32:33], v[160:161] op_sel_hi:[1,0]
	v_pk_mul_f32 v[34:35], v[34:35], v[160:161] op_sel_hi:[1,0]
	s_waitcnt lgkmcnt(0)
	v_pk_mul_f32 v[44:45], v[154:155], v[44:45]
	v_pk_mul_f32 v[46:47], v[156:157], v[46:47]
	v_pk_mul_f32 v[44:45], v[158:159], v[44:45]
	v_pk_mul_f32 v[46:47], v[76:77], v[46:47]
	v_cvt_pk_bf16_f32 v44, v44, v45
	v_cvt_pk_bf16_f32 v45, v46, v47
	global_store_dwordx2 v[68:69], v[44:45], off
	ds_read_b128 v[44:47], v254 offset:64
	v_lshlrev_b32_e32 v76, 16, v74
	v_and_b32_e32 v77, 0xffff0000, v74
	v_lshlrev_b32_e32 v74, 16, v75
	v_and_b32_e32 v75, 0xffff0000, v75
	v_mul_f32_e32 v154, 0xbfb8aa3b, v76
	v_mul_f32_e32 v155, 0xbfb8aa3b, v77
	v_mul_f32_e32 v156, 0xbfb8aa3b, v74
	v_mul_f32_e32 v157, 0xbfb8aa3b, v75
	v_exp_f32_e32 v154, v154
	v_exp_f32_e32 v155, v155
	v_exp_f32_e32 v156, v156
	v_exp_f32_e32 v157, v157
	v_add_f32_e32 v154, 1.0, v154
	v_add_f32_e32 v155, 1.0, v155
	v_add_f32_e32 v156, 1.0, v156
	v_add_f32_e32 v157, 1.0, v157
	v_rcp_f32_e32 v154, v154
	v_rcp_f32_e32 v155, v155
	v_rcp_f32_e32 v156, v156
	v_rcp_f32_e32 v157, v157
	v_pk_mul_f32 v[76:77], v[154:155], v[76:77]
	v_pk_mul_f32 v[74:75], v[156:157], v[74:75]
	s_waitcnt lgkmcnt(0)
	v_pk_mul_f32 v[40:41], v[44:45], v[40:41]
	v_pk_mul_f32 v[42:43], v[46:47], v[42:43]
	v_pk_mul_f32 v[40:41], v[76:77], v[40:41]
	v_pk_mul_f32 v[42:43], v[74:75], v[42:43]
	v_cvt_pk_bf16_f32 v40, v40, v41
	v_cvt_pk_bf16_f32 v41, v42, v43
	global_store_dwordx2 v[68:69], v[40:41], off offset:32
	ds_read_b128 v[40:43], v254 offset:128
	v_lshlrev_b32_e32 v44, 16, v72
	v_and_b32_e32 v45, 0xffff0000, v72
	v_lshlrev_b32_e32 v46, 16, v73
	v_and_b32_e32 v47, 0xffff0000, v73
	v_mul_f32_e32 v72, 0xbfb8aa3b, v44
	v_mul_f32_e32 v73, 0xbfb8aa3b, v45
	v_mul_f32_e32 v74, 0xbfb8aa3b, v46
	v_mul_f32_e32 v75, 0xbfb8aa3b, v47
	v_exp_f32_e32 v72, v72
	v_exp_f32_e32 v73, v73
	v_exp_f32_e32 v74, v74
	v_exp_f32_e32 v75, v75
	v_add_f32_e32 v72, 1.0, v72
	v_add_f32_e32 v73, 1.0, v73
	v_add_f32_e32 v74, 1.0, v74
	v_add_f32_e32 v75, 1.0, v75
	v_rcp_f32_e32 v72, v72
	v_rcp_f32_e32 v73, v73
	v_rcp_f32_e32 v74, v74
	v_rcp_f32_e32 v75, v75
	v_pk_mul_f32 v[44:45], v[72:73], v[44:45]
	v_pk_mul_f32 v[46:47], v[74:75], v[46:47]
	s_waitcnt lgkmcnt(0)
	v_pk_mul_f32 v[36:37], v[40:41], v[36:37]
	v_pk_mul_f32 v[38:39], v[42:43], v[38:39]
	v_pk_mul_f32 v[36:37], v[44:45], v[36:37]
	v_pk_mul_f32 v[38:39], v[46:47], v[38:39]
	v_cvt_pk_bf16_f32 v36, v36, v37
	v_cvt_pk_bf16_f32 v37, v38, v39
	global_store_dwordx2 v[68:69], v[36:37], off offset:64
	ds_read_b128 v[36:39], v254 offset:192
	v_lshlrev_b32_e32 v40, 16, v66
	v_and_b32_e32 v41, 0xffff0000, v66
	v_lshlrev_b32_e32 v42, 16, v67
	v_and_b32_e32 v43, 0xffff0000, v67
	v_mul_f32_e32 v44, 0xbfb8aa3b, v40
	v_mul_f32_e32 v45, 0xbfb8aa3b, v41
	v_mul_f32_e32 v46, 0xbfb8aa3b, v42
	v_mul_f32_e32 v47, 0xbfb8aa3b, v43
	v_exp_f32_e32 v44, v44
	v_exp_f32_e32 v45, v45
	v_exp_f32_e32 v46, v46
	v_exp_f32_e32 v47, v47
	v_add_f32_e32 v44, 1.0, v44
	v_add_f32_e32 v45, 1.0, v45
	v_add_f32_e32 v46, 1.0, v46
	v_add_f32_e32 v47, 1.0, v47
	v_rcp_f32_e32 v44, v44
	v_rcp_f32_e32 v45, v45
	v_rcp_f32_e32 v46, v46
	v_rcp_f32_e32 v47, v47
	v_pk_mul_f32 v[40:41], v[44:45], v[40:41]
	v_pk_mul_f32 v[42:43], v[46:47], v[42:43]
	s_waitcnt lgkmcnt(0)
	v_pk_mul_f32 v[32:33], v[36:37], v[32:33]
	v_pk_mul_f32 v[34:35], v[38:39], v[34:35]
	v_pk_mul_f32 v[32:33], v[40:41], v[32:33]
	v_pk_mul_f32 v[34:35], v[42:43], v[34:35]
	v_cvt_pk_bf16_f32 v32, v32, v33
	v_cvt_pk_bf16_f32 v33, v34, v35
	global_store_dwordx2 v[68:69], v[32:33], off offset:96

; #define LAS __attribute__((address_space(3)))
; #define SBAR() __builtin_amdgcn_sched_barrier(0)
; __device__ __forceinline__ int v_rd_base(int lane) { return ((lane & 3) << 3) | (((lane >> 2) & 3) << 6) | (((lane >> 4) & 1) << 5) | (((lane >> 5) & 1) << 8); }
; #define VMW() asm volatile("s_waitcnt vmcnt(0)" ::: "memory")
; #define SWRITE_HV(bf) do { int t_ = tid; LAUNDER(t_); const int vst0_ = v_st(t_ >> 4, (t_ & 15) * 8), vst1_ = v_st(32 + (t_ >> 4), (t_ & 15) * 8); \
;                            *(LAS bf16x8*)(lds + OFF_V + (bf) * SHM_V + vst0_) = S.st_v0; *(LAS bf16x8*)(lds + OFF_V + (bf) * SHM_V + vst1_) = S.st_v1; } while (0)
; #define SWRITE_H(bf) do { SWRITE_HV(bf); SWRITE_HK(bf); } while (0)
; #define Kh R_K(cur)
; #define Vh R_V(cur)
; #define Rh R_R(cur)
; #define MASKT(P0_, P1_, t) do { const int kb_ = KBASE(t); if (kb_ + KVBLK - 1 > qlo) mask_tile(P0_, P1_, qm - kb_); } while (0)
; __device__ __forceinline__ void attn_block(const Bases& B, const BlockRef& cur, const BlockRef& nxt, LAS char* lds, Seam& S, int tid) {
;     ...
;     float m_reg = -1e30f, l_reg = 0; f32x16 o[4] = {};
;     const int vb0 = (int)(unsigned)(uintptr_t)lds + v_rd_base(lane);
;     LAS char* qrb = lds + OFF_QR + wid * 4096 + lane * 16;
;     ...
;     f32x16 pA0, pA1, pB0, pB1; float mnA, mnB, alA, alB; bf16x8 pa0, pa1, pa2, pa3;
;     SWRITE_HV(0); SBAR();
;     if (NT > 1) { SLOAD_H(Kh, Vh, Rh, KBASE(1)); }
;     SBAR(); qkt<0>(pA0, pA1, lds, r32, hi, S.qr, qrb);
;     MASKT(pA0, pA1, 0); partialSM(pA0, pA1, m_reg, mnA, alA);
;     if (NT > 1) { VMW(); SWRITE_H(1); }
;     __syncthreads();
.LBB0_505:
	s_nop 8
	v_max_f32_e32 v0, v19, v19
	v_max_f32_e32 v54, v18, v18
	v_max_f32_e32 v0, v54, v0
	v_max3_f32 v0, v0, v20, v21
	v_max3_f32 v0, v0, v22, v23
	v_max3_f32 v0, v0, v24, v25
	v_max3_f32 v0, v0, v26, v27
	v_max3_f32 v0, v0, v28, v29
	v_max3_f32 v0, v0, v30, v31
	v_max3_f32 v0, v0, v32, v33
	v_max3_f32 v0, v0, v2, v3
	v_max3_f32 v0, v0, v4, v5
	v_max3_f32 v0, v0, v6, v7
	v_max3_f32 v0, v0, v8, v9
	v_max3_f32 v0, v0, v10, v11
	v_max3_f32 v0, v0, v12, v13
	v_max3_f32 v0, v0, v14, v15
	v_max3_f32 v0, v0, v16, v17
	v_mov_b32_e32 v54, v0
	s_nop 1
	v_permlane32_swap_b32_e32 v0, v54
	v_max_f32_e32 v54, v54, v54
	v_max_f32_e32 v0, v0, v0
	v_max_f32_e32 v0, v0, v54
	s_and_b32 s4, s4, 0x3fffffc0
	v_add_f32_e32 v54, 0x7149f2ca, v0
	s_lshl_b32 s4, s4, 2
	v_mul_f32_e32 v54, 0x3d93cd3a, v54
	v_max_f32_e32 v0, 0xf149f2ca, v0
	s_lshl_b32 s5, s86, 2
	s_add_i32 s4, s4, 0
	v_cmp_ge_f32_e32 vcc, s73, v54
	v_sub_f32_e32 v54, 0xf149f2ca, v0
	s_or_b32 s87, s5, 3
	s_add_i32 s4, s4, 0x19000
	v_mul_f32_e32 v54, 0x3dd53b94, v54
	v_exp_f32_e32 v54, v54
	s_cmp_eq_u64 vcc, exec
	s_cselect_b64 vcc, -1, 0
	v_cndmask_b32_e32 v185, v0, v175, vcc
	v_mul_f32_e32 v0, 0xbdd53b94, v185
	v_cndmask_b32_e64 v183, v54, 1.0, vcc
	v_fmamk_f32 v18, v18, 0x3dd53b94, v0
	v_fmamk_f32 v19, v19, 0x3dd53b94, v0
	v_fmamk_f32 v20, v20, 0x3dd53b94, v0
	v_fmamk_f32 v21, v21, 0x3dd53b94, v0
	v_fmamk_f32 v22, v22, 0x3dd53b94, v0
	v_fmamk_f32 v23, v23, 0x3dd53b94, v0
	v_fmamk_f32 v24, v24, 0x3dd53b94, v0
	v_fmamk_f32 v25, v25, 0x3dd53b94, v0
	v_fmamk_f32 v26, v26, 0x3dd53b94, v0
	v_fmamk_f32 v27, v27, 0x3dd53b94, v0
	v_fmamk_f32 v28, v28, 0x3dd53b94, v0
	v_fmamk_f32 v29, v29, 0x3dd53b94, v0
	v_fmamk_f32 v30, v30, 0x3dd53b94, v0
	v_fmamk_f32 v31, v31, 0x3dd53b94, v0
	v_fmamk_f32 v32, v32, 0x3dd53b94, v0
	v_mov_b32_e32 v54, v0
	v_pk_fma_f32 v[150:151], v[16:17], s[80:81], v[0:1] op_sel_hi:[1,0,0]
	v_pk_fma_f32 v[152:153], v[14:15], s[80:81], v[0:1] op_sel_hi:[1,0,0]
	v_pk_fma_f32 v[154:155], v[12:13], s[80:81], v[0:1] op_sel_hi:[1,0,0]
	v_pk_fma_f32 v[156:157], v[10:11], s[80:81], v[0:1] op_sel_hi:[1,0,0]
	v_pk_fma_f32 v[158:159], v[8:9], s[80:81], v[0:1] op_sel_hi:[1,0,0]
	v_pk_fma_f32 v[160:161], v[6:7], s[80:81], v[0:1] op_sel_hi:[1,0,0]
	v_pk_fma_f32 v[162:163], v[4:5], s[80:81], v[0:1] op_sel_hi:[1,0,0]
	v_pk_fma_f32 v[164:165], v[2:3], s[80:81], v[0:1] op_sel_hi:[1,0,0]
	v_mov_b32_e32 v0, v166
	s_waitcnt vmcnt(0)
	v_fmac_f32_e32 v54, 0x3dd53b94, v33
	v_ashrrev_i32_e32 v2, 4, v0
	v_and_b32_e32 v3, 0xfffff0, v2
	v_lshlrev_b32_e32 v4, 1, v2
	v_and_or_b32 v3, v4, 8, v3
	v_lshrrev_b32_e32 v4, 1, v2
	v_and_b32_e32 v6, 3, v2
	v_add_u32_e32 v2, 32, v2
	v_and_or_b32 v4, v4, 4, v6
	v_and_b32_e32 v6, 0xfffff0, v2
	v_lshlrev_b32_e32 v2, 1, v2
	v_and_or_b32 v2, v2, 8, v6
	v_lshrrev_b32_e32 v3, 1, v3
	v_bfe_u32 v5, v0, 2, 2
	v_lshrrev_b32_e32 v2, 1, v2
	v_or_b32_e32 v3, v3, v5
	v_lshlrev_b32_e32 v0, 4, v0
	v_or_b32_e32 v2, v2, v5
	v_lshlrev_b32_e32 v3, 9, v3
	v_and_b32_e32 v0, 48, v0
	v_lshlrev_b32_e32 v2, 9, v2
	v_lshl_add_u32 v4, v4, 6, 0
	v_add3_u32 v3, v4, v3, v0
	v_add3_u32 v0, v4, v2, v0
	s_waitcnt vmcnt(4)
	ds_write_b128 v3, v[42:45] offset:16384
	s_waitcnt vmcnt(2)
	ds_write_b128 v0, v[46:49] offset:16384
	v_mov_b32_e32 v0, v166
	v_exp_f32_e32 v205, v18
	v_lshrrev_b32_e32 v2, 4, v0
	v_lshlrev_b32_e32 v3, 4, v0
	v_lshrrev_b32_e32 v0, 3, v0
	v_mul_lo_u32 v2, v2, s1
	v_and_b32_e32 v4, 0xf0, v3
	v_mul_lo_u32 v0, v0, s0
	v_and_b32_e32 v3, 0x70, v3
	v_exp_f32_e32 v207, v19
	v_exp_f32_e32 v203, v20
	v_exp_f32_e32 v206, v21
	v_exp_f32_e32 v202, v22
	v_exp_f32_e32 v204, v23
	v_exp_f32_e32 v200, v24
	v_exp_f32_e32 v201, v25
	v_exp_f32_e32 v197, v26
	v_exp_f32_e32 v199, v27
	v_exp_f32_e32 v196, v28
	v_exp_f32_e32 v198, v29
	v_exp_f32_e32 v193, v30
	v_exp_f32_e32 v195, v31
	v_exp_f32_e32 v192, v32
	v_exp_f32_e32 v194, v54
	v_add3_u32 v2, s77, v2, v4
	v_add3_u32 v0, s72, v0, v3
	v_mov_b32_e32 v14, v1
	v_mov_b32_e32 v15, v1
	ds_write_b128 v2, v[34:37]
	s_waitcnt vmcnt(1)
	ds_write_b128 v2, v[38:41] offset:8704
	s_waitcnt vmcnt(0)
	ds_write_b128 v0, v[50:53]
	v_mov_b32_e32 v0, v1
	v_mov_b32_e32 v2, v1
	v_mov_b32_e32 v3, v1
	v_mov_b32_e32 v4, v1
	v_mov_b32_e32 v5, v1
	v_mov_b32_e32 v6, v1
	v_mov_b32_e32 v7, v1
	v_mov_b32_e32 v8, v1
	v_mov_b32_e32 v9, v1
	v_mov_b32_e32 v10, v1
	v_mov_b32_e32 v11, v1
	v_mov_b32_e32 v12, v1
	v_mov_b32_e32 v13, v1
	v_mov_b64_e32 v[64:65], v[14:15]
	v_mov_b64_e32 v[48:49], v[14:15]
	v_mov_b64_e32 v[32:33], v[14:15]
	v_mov_b64_e32 v[62:63], v[12:13]
	v_mov_b64_e32 v[60:61], v[10:11]
	v_mov_b64_e32 v[58:59], v[8:9]
	v_mov_b64_e32 v[56:57], v[6:7]
	v_mov_b64_e32 v[54:55], v[4:5]
	v_mov_b64_e32 v[52:53], v[2:3]
	v_mov_b64_e32 v[50:51], v[0:1]
	v_mov_b64_e32 v[46:47], v[12:13]
	v_mov_b64_e32 v[44:45], v[10:11]
	v_mov_b64_e32 v[42:43], v[8:9]
	v_mov_b64_e32 v[40:41], v[6:7]
	v_mov_b64_e32 v[38:39], v[4:5]
	v_mov_b64_e32 v[36:37], v[2:3]
	v_mov_b64_e32 v[34:35], v[0:1]
	v_mov_b64_e32 v[30:31], v[12:13]
	v_mov_b64_e32 v[28:29], v[10:11]
	v_mov_b64_e32 v[26:27], v[8:9]
	v_mov_b64_e32 v[24:25], v[6:7]
	v_mov_b64_e32 v[22:23], v[4:5]
	v_mov_b64_e32 v[20:21], v[2:3]
	v_mov_b64_e32 v[18:19], v[0:1]
	v_mov_b64_e32 v[16:17], v[14:15]
	s_mov_b32 s75, 1
	v_lshl_add_u32 v180, v167, 2, s4
	v_lshl_add_u32 v179, v168, 2, s4
	v_add_u32_e32 v184, s85, v171
	s_mov_b32 s74, 0
	v_mov_b32_e32 v181, 0
	s_movk_i32 s96, 0xe0
	v_mov_b64_e32 v[14:15], v[12:13]
	v_mov_b64_e32 v[12:13], v[10:11]
	v_mov_b64_e32 v[10:11], v[8:9]
	v_mov_b64_e32 v[8:9], v[6:7]
	v_mov_b64_e32 v[6:7], v[4:5]
	v_mov_b64_e32 v[4:5], v[2:3]
	v_mov_b64_e32 v[2:3], v[0:1]
	v_lshrrev_b32_e32 v243, 4, v166
	v_lshlrev_b32_e32 v244, 4, v166
	v_lshrrev_b32_e32 v242, 3, v166
	v_mul_u32_u24_e32 v243, 0x110, v243
	v_and_b32_e32 v245, 0xf0, v244
	v_mul_u32_u24_e32 v242, 0x90, v242
	v_and_b32_e32 v244, 0x70, v244
	v_add_u32_e32 v250, v243, v245
	v_add_u32_e32 v251, v242, v244
	v_mov_b32_e32 v242, v166
	v_ashrrev_i32_e32 v243, 4, v242
	v_and_b32_e32 v244, 0xfffff0, v243
	v_lshlrev_b32_e32 v245, 1, v243
	v_and_or_b32 v244, v245, 8, v244
	v_lshrrev_b32_e32 v245, 1, v243
	v_and_b32_e32 v247, 3, v243
	v_add_u32_e32 v243, 32, v243
	v_and_or_b32 v245, v245, 4, v247
	v_and_b32_e32 v247, 0xfffff0, v243
	v_lshlrev_b32_e32 v243, 1, v243
	v_and_or_b32 v243, v243, 8, v247
	v_lshrrev_b32_e32 v244, 1, v244
	v_bfe_u32 v246, v242, 2, 2
	v_lshrrev_b32_e32 v243, 1, v243
	v_or_b32_e32 v244, v244, v246
	v_lshlrev_b32_e32 v242, 4, v242
	v_or_b32_e32 v243, v243, v246
	v_lshlrev_b32_e32 v244, 9, v244
	v_and_b32_e32 v242, 48, v242
	v_lshlrev_b32_e32 v243, 9, v243
	v_lshlrev_b32_e32 v245, 6, v245
	v_add3_u32 v252, v245, v244, v242
	v_add3_u32 v253, v245, v243, v242
	s_waitcnt lgkmcnt(0)
	s_barrier
; #define LAS __attribute__((address_space(3)))
; __device__ __forceinline__ void finishSM(f32x16& p0, f32x16& p1, float alpha, float& l_reg, bf16x8& pa0, bf16x8& pa1, bf16x8& pa2, bf16x8& pa3) {
; #pragma unroll
;     for (int r = 0; r < 16; ++r) p1[r] = __builtin_amdgcn_exp2f(p1[r]);
;     float ps = 0;
; #pragma unroll
;     for (int r = 0; r < 16; ++r) ps += p0[r];
; #pragma unroll
;     for (int r = 0; r < 16; ++r) ps += p1[r];
;     { auto rr = __builtin_amdgcn_permlane32_swap(__float_as_uint(ps), __float_as_uint(ps), false, false);
;       ps = __uint_as_float(rr[0]) + __uint_as_float(rr[1]); }
;     l_reg = l_reg * alpha + ps;
;     ...
;     PK4(p0, 0, pa0); PK4(p0, 8, pa1); PK4(p1, 0, pa2); PK4(p1, 8, pa3);
;     ...
; }
; template <int KB>
; __device__ __forceinline__ void qkt(f32x16& p0, f32x16& p1, const LAS char* lds, int r32, int hi, const bf16x8* qr, const LAS char* qrb) {
;     p0 = f32x16{}; p1 = f32x16{};
;     { const LAS char* kbp = lds + OFF_K + KB * SHM_K + KSWZ(r32, hi * 16);
; #pragma unroll
;     for (int d0 = 0; d0 < 8; ++d0) { const LAS char* a = kbp + d0 * 32;
;         const bf16x8 b0 = *reinterpret_cast<const LAS bf16x8*>(a);
;         const bf16x8 b1 = *reinterpret_cast<const LAS bf16x8*>(a + 32 * 272);
;         p0 = __builtin_amdgcn_mfma_f32_32x32x16_bf16(b0, qr[d0], p0, 0, 0, 0);
;         p1 = __builtin_amdgcn_mfma_f32_32x32x16_bf16(b1, qr[d0], p1, 0, 0, 0); } }
;     { const LAS char* rb = lds + OFF_R + KB * SHM_R + RSWZ(r32, hi * 16);
; #pragma unroll
;     for (int d0 = 0; d0 < 4; ++d0) { const LAS char* a = rb + d0 * 32;
;         const bf16x8 b0 = *reinterpret_cast<const LAS bf16x8*>(a);
;         const bf16x8 b1 = *reinterpret_cast<const LAS bf16x8*>(a + 32 * 144);
;         const bf16x8 qv = *reinterpret_cast<const LAS bf16x8*>(qrb + d0 * 1024);
;         p0 = __builtin_amdgcn_mfma_f32_32x32x16_bf16(b0, qv, p0, 0, 0, 0);
;         p1 = __builtin_amdgcn_mfma_f32_32x32x16_bf16(b1, qv, p1, 0, 0, 0); } }
; }
.LBB0_506:
	ds_read_b128 v[66:69], v176
	ds_read_b128 v[130:133], v176 offset:32
	v_exp_f32_e32 v0, v164
	v_exp_f32_e32 v164, v165
	v_exp_f32_e32 v162, v162
	s_waitcnt lgkmcnt(1)
	v_mfma_f32_32x32x16_bf16 v[82:97], v[66:69], v[126:129], 0
	ds_read_b128 v[66:69], v176 offset:8704
	s_waitcnt vmcnt(2)
	ds_read_b128 v[134:137], v176 offset:8736
	v_exp_f32_e32 v163, v163
	v_exp_f32_e32 v160, v160
	v_exp_f32_e32 v165, v157
	v_exp_f32_e32 v190, v154
	v_exp_f32_e32 v191, v155
	s_waitcnt lgkmcnt(1)
	v_mfma_f32_32x32x16_bf16 v[66:81], v[66:69], v[126:129], 0
	v_mfma_f32_32x32x16_bf16 v[82:97], v[130:133], v[122:125], v[82:97]
	s_waitcnt lgkmcnt(0)
	v_mfma_f32_32x32x16_bf16 v[66:81], v[134:137], v[122:125], v[66:81]
	ds_read_b128 v[130:133], v176 offset:64
	ds_read_b128 v[134:137], v176 offset:96
	s_waitcnt lgkmcnt(1)
	v_mfma_f32_32x32x16_bf16 v[82:97], v[130:133], v[118:121], v[82:97]
	ds_read_b128 v[130:133], v176 offset:8768
	ds_read_b128 v[138:141], v176 offset:8800
	s_waitcnt lgkmcnt(1)
	v_mfma_f32_32x32x16_bf16 v[66:81], v[130:133], v[118:121], v[66:81]
	v_mfma_f32_32x32x16_bf16 v[82:97], v[134:137], v[114:117], v[82:97]
	ds_read_b128 v[130:133], v176 offset:128
	ds_read_b128 v[134:137], v176 offset:160
	s_waitcnt lgkmcnt(2)
	v_mfma_f32_32x32x16_bf16 v[66:81], v[138:141], v[114:117], v[66:81]
	s_waitcnt lgkmcnt(1)
	v_mfma_f32_32x32x16_bf16 v[82:97], v[130:133], v[110:113], v[82:97]
	ds_read_b128 v[130:133], v176 offset:8832
	ds_read_b128 v[138:141], v176 offset:8864
	s_waitcnt lgkmcnt(1)
	v_mfma_f32_32x32x16_bf16 v[66:81], v[130:133], v[110:113], v[66:81]
	ds_read_b128 v[130:133], v176 offset:192
	s_waitcnt vmcnt(1)
	ds_read_b128 v[142:145], v176 offset:224
	s_waitcnt vmcnt(0)
	ds_read_b128 v[146:149], v176 offset:8896
	ds_read_b128 v[186:189], v176 offset:8928
	ds_read_b128 v[210:213], v177
	ds_read_b128 v[214:217], v177 offset:32
	v_mfma_f32_32x32x16_bf16 v[82:97], v[134:137], v[106:109], v[82:97]
	ds_read_b128 v[134:137], v177 offset:4608
	ds_read_b128 v[218:221], v177 offset:4640
	ds_read_b128 v[222:225], v178
	ds_read_b128 v[226:229], v178 offset:1024
	ds_read_b128 v[230:233], v177 offset:64
	ds_read_b128 v[234:237], v177 offset:96
	ds_read_b128 v[238:241], v177 offset:4672
	ds_read_b128 v[242:245], v177 offset:4704
	s_waitcnt lgkmcnt(14)
	v_mfma_f32_32x32x16_bf16 v[66:81], v[138:141], v[106:109], v[66:81]
	ds_read_b128 v[138:141], v178 offset:2048
	ds_read_b128 v[246:249], v178 offset:3072
	s_waitcnt lgkmcnt(14)
	v_mfma_f32_32x32x16_bf16 v[82:97], v[130:133], v[102:105], v[82:97]
	v_exp_f32_e32 v130, v161
	v_exp_f32_e32 v131, v158
	v_exp_f32_e32 v132, v159
	v_exp_f32_e32 v133, v156
	s_waitcnt lgkmcnt(13)
	v_mfma_f32_32x32x16_bf16 v[66:81], v[146:149], v[102:105], v[66:81]
	v_exp_f32_e32 v148, v150
	v_add_f32_e32 v150, 0, v205
	v_add_f32_e32 v150, v207, v150
	v_add_f32_e32 v150, v203, v150
	v_exp_f32_e32 v146, v152
	v_exp_f32_e32 v147, v153
	v_exp_f32_e32 v149, v151
	v_mfma_f32_32x32x16_bf16 v[82:97], v[142:145], v[98:101], v[82:97]
	v_add_f32_e32 v142, v206, v150
	v_add_f32_e32 v142, v202, v142
	v_add_f32_e32 v142, v204, v142
	v_add_f32_e32 v142, v200, v142
	v_add_f32_e32 v142, v201, v142
	v_add_f32_e32 v142, v197, v142
	v_add_f32_e32 v142, v199, v142
	s_waitcnt lgkmcnt(12)
	v_mfma_f32_32x32x16_bf16 v[66:81], v[186:189], v[98:101], v[66:81]
	v_add_f32_e32 v142, v196, v142
	v_add_f32_e32 v142, v198, v142
	v_add_f32_e32 v142, v193, v142
	v_add_f32_e32 v142, v195, v142
	v_add_f32_e32 v142, v192, v142
	v_add_f32_e32 v142, v194, v142
	v_add_f32_e32 v142, v0, v142
	s_waitcnt lgkmcnt(7)
	v_mfma_f32_32x32x16_bf16 v[82:97], v[210:213], v[222:225], v[82:97]
	v_add_f32_e32 v142, v164, v142
	v_add_f32_e32 v142, v162, v142
	v_add_f32_e32 v142, v163, v142
	v_add_f32_e32 v142, v160, v142
	v_add_f32_e32 v142, v130, v142
	v_add_f32_e32 v142, v131, v142
	v_add_f32_e32 v142, v132, v142
	v_mfma_f32_32x32x16_bf16 v[66:81], v[134:137], v[222:225], v[66:81]
	v_add_f32_e32 v134, v133, v142
	v_add_f32_e32 v134, v165, v134
	v_add_f32_e32 v134, v190, v134
	v_add_f32_e32 v134, v191, v134
	v_add_f32_e32 v134, v146, v134
	v_add_f32_e32 v134, v147, v134
	v_add_f32_e32 v134, v148, v134
	s_waitcnt lgkmcnt(6)
	v_mfma_f32_32x32x16_bf16 v[82:97], v[214:217], v[226:229], v[82:97]
	v_add_f32_e32 v186, v149, v134
	v_mov_b32_e32 v187, v186
	s_nop 1
	v_permlane32_swap_b32_e32 v186, v187
	v_cvt_pk_bf16_f32 v150, v205, v207
	v_cvt_pk_bf16_f32 v151, v203, v206
	v_cvt_pk_bf16_f32 v152, v202, v204
	v_mfma_f32_32x32x16_bf16 v[66:81], v[218:221], v[226:229], v[66:81]
	v_cvt_pk_bf16_f32 v153, v200, v201
	v_cvt_pk_bf16_f32 v154, v197, v199
	v_cvt_pk_bf16_f32 v155, v196, v198
	v_cvt_pk_bf16_f32 v156, v193, v195
	v_cvt_pk_bf16_f32 v157, v192, v194
	v_cvt_pk_bf16_f32 v158, v0, v164
	v_cvt_pk_bf16_f32 v159, v162, v163
	s_waitcnt lgkmcnt(1)
	v_mfma_f32_32x32x16_bf16 v[82:97], v[230:233], v[138:141], v[82:97]
	v_cvt_pk_bf16_f32 v160, v160, v130
	v_cvt_pk_bf16_f32 v161, v131, v132
	v_cvt_pk_bf16_f32 v162, v133, v165
	v_cvt_pk_bf16_f32 v163, v190, v191
	v_cvt_pk_bf16_f32 v164, v146, v147
	v_cvt_pk_bf16_f32 v165, v148, v149
	v_permlane32_swap_b32_e32 v150, v152
	v_mfma_f32_32x32x16_bf16 v[66:81], v[238:241], v[138:141], v[66:81]
	v_permlane32_swap_b32_e32 v151, v153
	v_permlane32_swap_b32_e32 v154, v156
	v_permlane32_swap_b32_e32 v155, v157
	v_permlane32_swap_b32_e32 v158, v160
	s_waitcnt lgkmcnt(0)
	v_mfma_f32_32x32x16_bf16 v[82:97], v[234:237], v[246:249], v[82:97]
	v_permlane32_swap_b32_e32 v159, v161
	v_permlane32_swap_b32_e32 v162, v164
	v_permlane32_swap_b32_e32 v163, v165
	v_mfma_f32_32x32x16_bf16 v[66:81], v[242:245], v[246:249], v[66:81]
	s_add_i32 s78, s96, 0xffffffa0
	v_mov_b32_e32 v0, v166
	s_lshl_b64 s[4:5], s[78:79], 12
	s_add_u32 s4, s92, s4
	v_lshlrev_b32_e32 v130, 8, v0
	v_lshlrev_b32_e32 v0, 4, v0
	s_addc_u32 s5, s93, s5
	s_sub_i32 s10, s96, 64
	s_mov_b32 s11, s79
	v_and_b32_e32 v131, 0xf0, v0
	s_lshl_b64 s[10:11], s[10:11], 12
	v_and_or_b32 v142, v130, s33, v131
	s_add_u32 s10, s92, s10
	s_addc_u32 s11, s93, s11
	global_load_dwordx4 v[130:133], v142, s[4:5] offset:256
	global_load_dwordx4 v[138:141], v142, s[4:5]
	global_load_dwordx4 v[134:137], v142, s[10:11] offset:256
	s_nop 0
	global_load_dwordx4 v[142:145], v142, s[10:11]
	s_lshl_b64 s[4:5], s[78:79], 7
	s_add_u32 s4, s94, s4
	s_addc_u32 s5, s95, s5
	global_load_dwordx4 v[146:149], v0, s[4:5]
	s_add_i32 s5, s96, 0xffffff9f
	s_cmp_le_i32 s5, s85
	s_cbranch_scc0 .Lattn_slow1
; __device__ __forceinline__ void partialSM(f32x16& p0, f32x16& p1, float& m_reg, float& mn, float& alpha) {
;     float pmax = p0[0];
; #pragma unroll
;     for (int r = 1; r < 16; ++r) pmax = fmaxf(pmax, p0[r]);
; #pragma unroll
;     for (int r = 0; r < 16; ++r) pmax = fmaxf(pmax, p1[r]);
;     { auto rr = __builtin_amdgcn_permlane32_swap(__float_as_uint(pmax), __float_as_uint(pmax), false, false);
;       pmax = fmaxf(__uint_as_float(rr[0]), __uint_as_float(rr[1])); }
;     constexpr float C2 = 1.4426950408889634f * ATT_SCALE;
;     if (__builtin_expect(__all((pmax - m_reg) * ATT_SCALE <= THR), 1)) { mn = m_reg; alpha = 1.f; }
;     else { mn = fmaxf(m_reg, pmax); alpha = __builtin_amdgcn_exp2f((m_reg - mn) * C2); m_reg = mn; }
;     const float mnL = -mn * C2;
; #pragma unroll
;     for (int r = 0; r < 16; ++r) p0[r] = fmaf(p0[r], C2, mnL);
; #pragma unroll
;     for (int r = 0; r < 16; ++r) p1[r] = fmaf(p1[r], C2, mnL);
; #pragma unroll
;     for (int r = 0; r < 16; ++r) p0[r] = __builtin_amdgcn_exp2f(p0[r]);
; }
	s_lshl_b32 s4, s74, 14
	v_add_u32_e32 v242, s4, v169
	ds_read_b64_tr_b16 v[222:223], v242 offset:0
	ds_read_b64_tr_b16 v[224:225], v242 offset:0x800
	ds_read_b64_tr_b16 v[226:227], v242 offset:0x1000
	ds_read_b64_tr_b16 v[228:229], v242 offset:0x1800
	ds_read_b64_tr_b16 v[230:231], v242 offset:0x2000
	ds_read_b64_tr_b16 v[232:233], v242 offset:0x2800
	ds_read_b64_tr_b16 v[234:235], v242 offset:0x3000
	ds_read_b64_tr_b16 v[236:237], v242 offset:0x3800
	v_max_f32_e32 v0, v83, v83
	v_max_f32_e32 v243, v82, v82
	v_max_f32_e32 v0, v243, v0
	v_max3_f32 v0, v0, v84, v85
	s_waitcnt lgkmcnt(0)
	s_nop 0
	v_mfma_f32_32x32x16_bf16 v[50:65], v[150:153], v[222:225], v[50:65]
	ds_read_b64_tr_b16 v[222:223], v242 offset:0x200
	ds_read_b64_tr_b16 v[224:225], v242 offset:0xa00
	v_max3_f32 v0, v0, v86, v87
	v_max3_f32 v0, v0, v88, v89
	v_max3_f32 v0, v0, v90, v91
	v_max3_f32 v0, v0, v92, v93
	v_max3_f32 v0, v0, v94, v95
	v_max3_f32 v0, v0, v96, v97
	v_max3_f32 v0, v0, v66, v67
	v_mfma_f32_32x32x16_bf16 v[50:65], v[154:157], v[226:229], v[50:65]
	ds_read_b64_tr_b16 v[226:227], v242 offset:0x1200
	ds_read_b64_tr_b16 v[228:229], v242 offset:0x1a00
	v_max3_f32 v0, v0, v68, v69
	v_max3_f32 v0, v0, v70, v71
	v_max3_f32 v0, v0, v72, v73
	v_max3_f32 v0, v0, v74, v75
	v_max3_f32 v0, v0, v76, v77
	v_max3_f32 v0, v0, v78, v79
	v_mfma_f32_32x32x16_bf16 v[50:65], v[158:161], v[230:233], v[50:65]
	ds_read_b64_tr_b16 v[230:231], v242 offset:0x2200
	ds_read_b64_tr_b16 v[232:233], v242 offset:0x2a00
	ds_read_b64_tr_b16 v[238:239], v242 offset:0x3200
	ds_read_b64_tr_b16 v[240:241], v242 offset:0x3a00
	v_max3_f32 v0, v0, v80, v81
	v_mov_b32_e32 v243, v0
	s_nop 1
	v_permlane32_swap_b32_e32 v0, v243
	v_max_f32_e32 v243, v243, v243
	v_max_f32_e32 v0, v0, v0
	v_max_f32_e32 v0, v0, v243
	s_waitcnt lgkmcnt(0)
	v_mfma_f32_32x32x16_bf16 v[50:65], v[162:165], v[234:237], v[50:65]
	v_max_f32_e32 v244, v185, v185
	v_sub_f32_e32 v243, v0, v185
	v_max_f32_e32 v0, v244, v0
	v_sub_f32_e32 v244, v185, v0
	v_mul_f32_e32 v244, 0x3dd53b94, v244
	v_mul_f32_e32 v243, 0x3d93cd3a, v243
	v_exp_f32_e32 v244, v244
	v_mfma_f32_32x32x16_bf16 v[34:49], v[150:153], v[222:225], v[34:49]
	ds_read_b64_tr_b16 v[222:223], v242 offset:0x400
	ds_read_b64_tr_b16 v[224:225], v242 offset:0xc00
	v_cmp_ge_f32_e32 vcc, s73, v243
	s_cmp_eq_u64 vcc, exec
	s_cselect_b64 s[10:11], -1, 0
	v_cndmask_b32_e64 v189, v244, 1.0, s[10:11]
	v_cndmask_b32_e64 v0, v0, v185, s[10:11]
	v_mul_f32_e32 v185, 0xbdd53b94, v0
	v_mfma_f32_32x32x16_bf16 v[34:49], v[154:157], v[226:229], v[34:49]
	ds_read_b64_tr_b16 v[226:227], v242 offset:0x1400
	ds_read_b64_tr_b16 v[228:229], v242 offset:0x1c00
	v_fmamk_f32 v82, v82, 0x3dd53b94, v185
	v_fmamk_f32 v83, v83, 0x3dd53b94, v185
	v_fmamk_f32 v84, v84, 0x3dd53b94, v185
	v_fmamk_f32 v85, v85, 0x3dd53b94, v185
	v_fmamk_f32 v86, v86, 0x3dd53b94, v185
	v_fmamk_f32 v87, v87, 0x3dd53b94, v185
	v_fmamk_f32 v88, v88, 0x3dd53b94, v185
	v_mfma_f32_32x32x16_bf16 v[34:49], v[158:161], v[230:233], v[34:49]
	ds_read_b64_tr_b16 v[230:231], v242 offset:0x2400
	ds_read_b64_tr_b16 v[232:233], v242 offset:0x2c00
	ds_read_b64_tr_b16 v[234:235], v242 offset:0x3400
	ds_read_b64_tr_b16 v[236:237], v242 offset:0x3c00
	v_fmamk_f32 v89, v89, 0x3dd53b94, v185
	v_fmamk_f32 v90, v90, 0x3dd53b94, v185
	v_fmamk_f32 v91, v91, 0x3dd53b94, v185
	v_fmamk_f32 v92, v92, 0x3dd53b94, v185
	v_fmamk_f32 v93, v93, 0x3dd53b94, v185
	v_fmamk_f32 v94, v94, 0x3dd53b94, v185
	s_waitcnt lgkmcnt(0)
	v_mfma_f32_32x32x16_bf16 v[34:49], v[162:165], v[238:241], v[34:49]
	v_fmamk_f32 v95, v95, 0x3dd53b94, v185
	v_fmamk_f32 v96, v96, 0x3dd53b94, v185
	v_fmamk_f32 v97, v97, 0x3dd53b94, v185
	v_fmamk_f32 v190, v67, 0x3dd53b94, v185
	v_fmamk_f32 v191, v68, 0x3dd53b94, v185
	v_fmamk_f32 v188, v66, 0x3dd53b94, v185
	v_mfma_f32_32x32x16_bf16 v[18:33], v[150:153], v[222:225], v[18:33]
	ds_read_b64_tr_b16 v[222:223], v242 offset:0x600
	ds_read_b64_tr_b16 v[224:225], v242 offset:0xe00
	v_fmamk_f32 v192, v69, 0x3dd53b94, v185
	v_fmamk_f32 v193, v70, 0x3dd53b94, v185
	v_fmamk_f32 v194, v71, 0x3dd53b94, v185
	v_fmamk_f32 v195, v72, 0x3dd53b94, v185
	v_fmamk_f32 v196, v73, 0x3dd53b94, v185
	v_fmamk_f32 v197, v74, 0x3dd53b94, v185
	v_fmamk_f32 v198, v75, 0x3dd53b94, v185
	v_mfma_f32_32x32x16_bf16 v[18:33], v[154:157], v[226:229], v[18:33]
	ds_read_b64_tr_b16 v[226:227], v242 offset:0x1600
	ds_read_b64_tr_b16 v[228:229], v242 offset:0x1e00
	v_fmamk_f32 v199, v76, 0x3dd53b94, v185
	v_fmamk_f32 v200, v77, 0x3dd53b94, v185
	v_fmamk_f32 v201, v78, 0x3dd53b94, v185
	v_fmamk_f32 v202, v79, 0x3dd53b94, v185
	v_fmamk_f32 v203, v80, 0x3dd53b94, v185
	v_fmac_f32_e32 v185, 0x3dd53b94, v81
	v_mfma_f32_32x32x16_bf16 v[18:33], v[158:161], v[230:233], v[18:33]
	ds_read_b64_tr_b16 v[230:231], v242 offset:0x2600
	ds_read_b64_tr_b16 v[232:233], v242 offset:0x2e00
	ds_read_b64_tr_b16 v[238:239], v242 offset:0x3600
	ds_read_b64_tr_b16 v[240:241], v242 offset:0x3e00
	v_exp_f32_e32 v204, v82
	v_exp_f32_e32 v205, v83
	v_exp_f32_e32 v206, v84
	v_exp_f32_e32 v207, v85
	s_waitcnt lgkmcnt(0)
	v_mfma_f32_32x32x16_bf16 v[18:33], v[162:165], v[234:237], v[18:33]
	v_exp_f32_e32 v209, v86
	v_exp_f32_e32 v210, v87
	v_exp_f32_e32 v211, v88
	v_mfma_f32_32x32x16_bf16 v[2:17], v[150:153], v[222:225], v[2:17]
	v_exp_f32_e32 v212, v89
	v_exp_f32_e32 v213, v90
	v_exp_f32_e32 v214, v91
	v_mfma_f32_32x32x16_bf16 v[2:17], v[154:157], v[226:229], v[2:17]
	v_exp_f32_e32 v215, v92
	v_exp_f32_e32 v216, v93
	v_exp_f32_e32 v217, v94
	v_mfma_f32_32x32x16_bf16 v[2:17], v[158:161], v[230:233], v[2:17]
	v_exp_f32_e32 v218, v95
	v_exp_f32_e32 v219, v96
	v_exp_f32_e32 v220, v97
	v_mfma_f32_32x32x16_bf16 v[2:17], v[162:165], v[238:241], v[2:17]
	s_waitcnt vmcnt(3)
	ds_write_b128 v250, v[138:141] offset:49152
	s_waitcnt vmcnt(1)
	ds_write_b128 v250, v[142:145] offset:57856
	s_waitcnt vmcnt(0)
	v_add_u32_e32 v150, s76, v251
	ds_write_b128 v150, v[146:149]
	s_addk_i32 s4, 0xc000
	s_cmp_lg_u32 s74, 0
	s_cselect_b32 s4, s4, 0x8000
	v_add_u32_e32 v151, s4, v252
	v_add_u32_e32 v152, s4, v253
	v_cmp_gt_f32_e32 vcc, 1.0, v189
	ds_write_b128 v151, v[130:133]
	ds_write_b128 v152, v[134:137]
	s_cbranch_vccz .Lattn_f1_norsc
	s_and_saveexec_b64 s[4:5], s[8:9]
	ds_write_b32 v180, v189 offset:128
	s_or_b64 exec, exec, s[4:5]
	s_waitcnt lgkmcnt(0)
	ds_read_b128 v[150:153], v179 offset:224
	ds_read_b128 v[154:157], v179 offset:192
	ds_read_b128 v[158:161], v179 offset:160
	ds_read_b128 v[162:165], v179 offset:128
	s_waitcnt lgkmcnt(3)
	v_pk_mul_f32 v[64:65], v[64:65], v[152:153]
	s_waitcnt lgkmcnt(2)
	v_pk_mul_f32 v[60:61], v[60:61], v[156:157]
	s_waitcnt lgkmcnt(1)
	v_pk_mul_f32 v[56:57], v[56:57], v[160:161]
	s_waitcnt lgkmcnt(0)
	v_pk_mul_f32 v[52:53], v[52:53], v[164:165]
	v_pk_mul_f32 v[62:63], v[62:63], v[150:151]
	v_pk_mul_f32 v[58:59], v[58:59], v[154:155]
	v_pk_mul_f32 v[54:55], v[54:55], v[158:159]
	v_pk_mul_f32 v[50:51], v[50:51], v[162:163]
	v_pk_mul_f32 v[48:49], v[48:49], v[152:153]
	v_pk_mul_f32 v[44:45], v[44:45], v[156:157]
	v_pk_mul_f32 v[40:41], v[40:41], v[160:161]
	v_pk_mul_f32 v[36:37], v[36:37], v[164:165]
	v_pk_mul_f32 v[46:47], v[46:47], v[150:151]
	v_pk_mul_f32 v[42:43], v[42:43], v[154:155]
	v_pk_mul_f32 v[38:39], v[38:39], v[158:159]
	v_pk_mul_f32 v[34:35], v[34:35], v[162:163]
	v_pk_mul_f32 v[32:33], v[32:33], v[152:153]
	v_pk_mul_f32 v[28:29], v[28:29], v[156:157]
	v_pk_mul_f32 v[24:25], v[24:25], v[160:161]
	v_pk_mul_f32 v[20:21], v[20:21], v[164:165]
	v_pk_mul_f32 v[30:31], v[30:31], v[150:151]
	v_pk_mul_f32 v[26:27], v[26:27], v[154:155]
	v_pk_mul_f32 v[22:23], v[22:23], v[158:159]
	v_pk_mul_f32 v[18:19], v[18:19], v[162:163]
	v_pk_mul_f32 v[16:17], v[16:17], v[152:153]
	v_pk_mul_f32 v[12:13], v[12:13], v[156:157]
	v_pk_mul_f32 v[8:9], v[8:9], v[160:161]
	v_pk_mul_f32 v[4:5], v[4:5], v[164:165]
	v_pk_mul_f32 v[14:15], v[14:15], v[150:151]
	v_pk_mul_f32 v[10:11], v[10:11], v[154:155]
	v_pk_mul_f32 v[6:7], v[6:7], v[158:159]
	v_pk_mul_f32 v[2:3], v[2:3], v[162:163]

; __device__ __forceinline__ void partialSM(f32x16& p0, f32x16& p1, float& m_reg, float& mn, float& alpha) {
;     float pmax = p0[0];
; #pragma unroll
;     for (int r = 1; r < 16; ++r) pmax = fmaxf(pmax, p0[r]);
; #pragma unroll
;     for (int r = 0; r < 16; ++r) pmax = fmaxf(pmax, p1[r]);
;     { auto rr = __builtin_amdgcn_permlane32_swap(__float_as_uint(pmax), __float_as_uint(pmax), false, false);
;       pmax = fmaxf(__uint_as_float(rr[0]), __uint_as_float(rr[1])); }
;     constexpr float C2 = 1.4426950408889634f * ATT_SCALE;
;     if (__builtin_expect(__all((pmax - m_reg) * ATT_SCALE <= THR), 1)) { mn = m_reg; alpha = 1.f; }
;     else { mn = fmaxf(m_reg, pmax); alpha = __builtin_amdgcn_exp2f((m_reg - mn) * C2); m_reg = mn; }
;     const float mnL = -mn * C2;
; #pragma unroll
;     for (int r = 0; r < 16; ++r) p0[r] = fmaf(p0[r], C2, mnL);
; #pragma unroll
;     for (int r = 0; r < 16; ++r) p1[r] = fmaf(p1[r], C2, mnL);
; #pragma unroll
;     for (int r = 0; r < 16; ++r) p0[r] = __builtin_amdgcn_exp2f(p0[r]);
; }
; __device__ __forceinline__ void finishSM(f32x16& p0, f32x16& p1, float alpha, float& l_reg, bf16x8& pa0, bf16x8& pa1, bf16x8& pa2, bf16x8& pa3) {
; #pragma unroll
;     for (int r = 0; r < 16; ++r) p1[r] = __builtin_amdgcn_exp2f(p1[r]);
;     float ps = 0;
; #pragma unroll
;     for (int r = 0; r < 16; ++r) ps += p0[r];
; #pragma unroll
;     for (int r = 0; r < 16; ++r) ps += p1[r];
;     { auto rr = __builtin_amdgcn_permlane32_swap(__float_as_uint(ps), __float_as_uint(ps), false, false);
;       ps = __uint_as_float(rr[0]) + __uint_as_float(rr[1]); }
;     l_reg = l_reg * alpha + ps;
; __device__ __forceinline__ void attn_block(const Bases& B, const BlockRef& cur, const BlockRef& nxt, LAS char* lds, Seam& S, int tid) {
;     ...
;     for (int t = 1; t + 1 < NT; t += 2) {
;         HALF_STEP(pB0, pB1, mnB, alB, pA0, pA1, alA, t, 1, 0);
;         HALF_STEP(pA0, pA1, mnA, alA, pB0, pB1, alB, t + 1, 0, 1);
.LBB0_514:
	s_sub_i32 s10, s96, 33
	s_cmp_le_i32 s10, s85
	s_cbranch_scc0 .Lattn_slow2
	s_add_i32 s10, s74, 1
	s_cmp_lg_u32 s74, 2
	s_cselect_b32 s74, s10, 0
	s_lshl_b32 s78, s74, 14
	v_add_u32_e32 v242, s78, v169
	ds_read_b64_tr_b16 v[222:223], v242 offset:0
	ds_read_b64_tr_b16 v[224:225], v242 offset:0x800
	ds_read_b64_tr_b16 v[226:227], v242 offset:0x1000
	ds_read_b64_tr_b16 v[228:229], v242 offset:0x1800
	ds_read_b64_tr_b16 v[230:231], v242 offset:0x2000
	ds_read_b64_tr_b16 v[232:233], v242 offset:0x2800
	ds_read_b64_tr_b16 v[234:235], v242 offset:0x3000
	ds_read_b64_tr_b16 v[236:237], v242 offset:0x3800
	v_max_f32_e32 v243, v83, v83
	v_max_f32_e32 v244, v82, v82
	v_max_f32_e32 v243, v244, v243
	v_max3_f32 v243, v243, v84, v85
	s_waitcnt lgkmcnt(0)
	s_nop 0
	v_mfma_f32_32x32x16_bf16 v[50:65], v[150:153], v[222:225], v[50:65]
	ds_read_b64_tr_b16 v[222:223], v242 offset:0x200
	ds_read_b64_tr_b16 v[224:225], v242 offset:0xa00
	v_max3_f32 v243, v243, v86, v87
	v_max3_f32 v243, v243, v88, v89
	v_max3_f32 v243, v243, v90, v91
	v_max3_f32 v243, v243, v92, v93
	v_max3_f32 v243, v243, v94, v95
	v_max3_f32 v243, v243, v96, v97
	v_mfma_f32_32x32x16_bf16 v[50:65], v[154:157], v[226:229], v[50:65]
	ds_read_b64_tr_b16 v[226:227], v242 offset:0x1200
	ds_read_b64_tr_b16 v[228:229], v242 offset:0x1a00
	v_max3_f32 v243, v243, v66, v67
	v_max3_f32 v243, v243, v68, v69
	v_max3_f32 v243, v243, v70, v71
	v_max3_f32 v243, v243, v72, v73
	v_max3_f32 v243, v243, v74, v75
	v_mfma_f32_32x32x16_bf16 v[50:65], v[158:161], v[230:233], v[50:65]
	ds_read_b64_tr_b16 v[230:231], v242 offset:0x2200
	ds_read_b64_tr_b16 v[232:233], v242 offset:0x2a00
	ds_read_b64_tr_b16 v[238:239], v242 offset:0x3200
	ds_read_b64_tr_b16 v[240:241], v242 offset:0x3a00
	v_max3_f32 v243, v243, v76, v77
	v_max3_f32 v243, v243, v78, v79
	v_max3_f32 v243, v243, v80, v81
	v_mov_b32_e32 v244, v243
	s_nop 1
	v_permlane32_swap_b32_e32 v243, v244
	v_max_f32_e32 v244, v244, v244
	s_waitcnt lgkmcnt(0)
	v_mfma_f32_32x32x16_bf16 v[50:65], v[162:165], v[234:237], v[50:65]
	v_max_f32_e32 v243, v243, v243
	v_max_f32_e32 v243, v243, v244
	v_sub_f32_e32 v244, v243, v0
	v_mul_f32_e32 v244, 0x3d93cd3a, v244
	v_cmp_ge_f32_e32 vcc, s73, v244
	s_cmp_eq_u64 vcc, exec
	v_mfma_f32_32x32x16_bf16 v[34:49], v[150:153], v[222:225], v[34:49]
	ds_read_b64_tr_b16 v[222:223], v242 offset:0x400
	ds_read_b64_tr_b16 v[224:225], v242 offset:0xc00
	s_cselect_b64 s[10:11], -1, 0
	v_max_f32_e32 v245, v0, v0
	v_max_f32_e32 v245, v245, v243
	v_sub_f32_e32 v246, v0, v245
	v_mul_f32_e32 v246, 0x3dd53b94, v246
	v_exp_f32_e32 v246, v246
	v_mfma_f32_32x32x16_bf16 v[34:49], v[154:157], v[226:229], v[34:49]
	ds_read_b64_tr_b16 v[226:227], v242 offset:0x1400
	ds_read_b64_tr_b16 v[228:229], v242 offset:0x1c00
	s_nop 0
	v_cndmask_b32_e64 v188, v246, 1.0, s[10:11]
	v_cndmask_b32_e64 v185, v245, v0, s[10:11]
	v_mul_f32_e32 v0, 0xbdd53b94, v185
	v_fmamk_f32 v82, v82, 0x3dd53b94, v0
	v_fmamk_f32 v83, v83, 0x3dd53b94, v0
	v_mfma_f32_32x32x16_bf16 v[34:49], v[158:161], v[230:233], v[34:49]
	ds_read_b64_tr_b16 v[230:231], v242 offset:0x2400
	ds_read_b64_tr_b16 v[232:233], v242 offset:0x2c00
	ds_read_b64_tr_b16 v[234:235], v242 offset:0x3400
	ds_read_b64_tr_b16 v[236:237], v242 offset:0x3c00
	v_fmamk_f32 v84, v84, 0x3dd53b94, v0
	v_fmamk_f32 v85, v85, 0x3dd53b94, v0
	v_fmamk_f32 v86, v86, 0x3dd53b94, v0
	v_fmamk_f32 v87, v87, 0x3dd53b94, v0
	v_fmamk_f32 v88, v88, 0x3dd53b94, v0
	s_waitcnt lgkmcnt(0)
	v_mfma_f32_32x32x16_bf16 v[34:49], v[162:165], v[238:241], v[34:49]
	v_fmamk_f32 v89, v89, 0x3dd53b94, v0
	v_fmamk_f32 v90, v90, 0x3dd53b94, v0
	v_fmamk_f32 v91, v91, 0x3dd53b94, v0
	v_fmamk_f32 v92, v92, 0x3dd53b94, v0
	v_fmamk_f32 v93, v93, 0x3dd53b94, v0
	v_fmamk_f32 v94, v94, 0x3dd53b94, v0
	v_mfma_f32_32x32x16_bf16 v[18:33], v[150:153], v[222:225], v[18:33]
	ds_read_b64_tr_b16 v[222:223], v242 offset:0x600
	ds_read_b64_tr_b16 v[224:225], v242 offset:0xe00
	v_fmamk_f32 v95, v95, 0x3dd53b94, v0
	v_fmamk_f32 v96, v96, 0x3dd53b94, v0
	v_fmamk_f32 v97, v97, 0x3dd53b94, v0
	v_exp_f32_e32 v205, v82
	v_exp_f32_e32 v207, v83
	v_mfma_f32_32x32x16_bf16 v[18:33], v[154:157], v[226:229], v[18:33]
	ds_read_b64_tr_b16 v[226:227], v242 offset:0x1600
	ds_read_b64_tr_b16 v[228:229], v242 offset:0x1e00
	v_exp_f32_e32 v203, v84
	v_exp_f32_e32 v206, v85
	v_exp_f32_e32 v202, v86
	v_mfma_f32_32x32x16_bf16 v[18:33], v[158:161], v[230:233], v[18:33]
	ds_read_b64_tr_b16 v[230:231], v242 offset:0x2600
	ds_read_b64_tr_b16 v[232:233], v242 offset:0x2e00
	ds_read_b64_tr_b16 v[238:239], v242 offset:0x3600
	ds_read_b64_tr_b16 v[240:241], v242 offset:0x3e00
	v_exp_f32_e32 v204, v87
	v_exp_f32_e32 v200, v88
	s_waitcnt lgkmcnt(0)
	v_mfma_f32_32x32x16_bf16 v[18:33], v[162:165], v[234:237], v[18:33]
	v_exp_f32_e32 v201, v89
	v_exp_f32_e32 v197, v90
	v_exp_f32_e32 v199, v91
	v_mfma_f32_32x32x16_bf16 v[2:17], v[150:153], v[222:225], v[2:17]
	v_pk_fma_f32 v[152:153], v[78:79], s[80:81], v[0:1] op_sel_hi:[1,0,0]
	v_pk_fma_f32 v[150:151], v[80:81], s[80:81], v[0:1] op_sel_hi:[1,0,0]
	v_exp_f32_e32 v196, v92
	v_exp_f32_e32 v198, v93
	v_exp_f32_e32 v193, v94
	v_mfma_f32_32x32x16_bf16 v[2:17], v[154:157], v[226:229], v[2:17]
	v_pk_fma_f32 v[156:157], v[74:75], s[80:81], v[0:1] op_sel_hi:[1,0,0]
	v_pk_fma_f32 v[154:155], v[76:77], s[80:81], v[0:1] op_sel_hi:[1,0,0]
	v_exp_f32_e32 v195, v95
	v_exp_f32_e32 v192, v96
	v_exp_f32_e32 v194, v97
	v_mfma_f32_32x32x16_bf16 v[2:17], v[158:161], v[230:233], v[2:17]
	v_pk_fma_f32 v[160:161], v[70:71], s[80:81], v[0:1] op_sel_hi:[1,0,0]
	v_pk_fma_f32 v[158:159], v[72:73], s[80:81], v[0:1] op_sel_hi:[1,0,0]
	v_add_f32_e32 v247, v186, v187
	v_fmac_f32_e32 v247, v183, v181
	v_add_f32_e32 v181, v190, v191
	v_fmac_f32_e32 v181, v247, v189
	v_add_u32_e32 v184, 0xffffff80, v184
	v_mfma_f32_32x32x16_bf16 v[2:17], v[162:165], v[238:241], v[2:17]
	v_pk_fma_f32 v[164:165], v[66:67], s[80:81], v[0:1] op_sel_hi:[1,0,0]
	v_pk_fma_f32 v[162:163], v[68:69], s[80:81], v[0:1] op_sel_hi:[1,0,0]
	s_andn2_b64 vcc, exec, s[4:5]
	s_cbranch_vccnz .Lattn_f2_nostage
	s_waitcnt vmcnt(3)
	v_add_u32_e32 v243, s77, v250
	ds_write_b128 v243, v[138:141]
	s_waitcnt vmcnt(1)
	ds_write_b128 v243, v[142:145] offset:8704
	s_waitcnt vmcnt(0)
	v_add_u32_e32 v244, s72, v251
	ds_write_b128 v244, v[146:149]
	s_addk_i32 s78, 0xc000
	s_cmp_lg_u32 s74, 0
	s_cselect_b32 s4, s78, 0x8000
	v_add_u32_e32 v245, s4, v252
	v_add_u32_e32 v246, s4, v253
	ds_write_b128 v245, v[130:133]
	ds_write_b128 v246, v[134:137]
